# speedup vs baseline: 1.0199x; 1.0038x over previous
; __device__ __forceinline__ float sigm(float x) { return __builtin_amdgcn_rcpf(1.f + __expf(-x)); }
; __device__ __forceinline__ void gemm_glu_merge(u16* __restrict__ proj, const u16* __restrict__ Wt) {
;     ...
; #pragma unroll
;     for (int ai = 0; ai < 2; ++ai)
; #pragma unroll
;       for (int m = 0; m < 4; ++m)
; #pragma unroll
;         for (int j = 0; j < 4; ++j) {
;           const int row = ai * 128 + wr * 64 + m * 16 + fq * 4 + j;
;           u16* pr = proj + (size_t)row * 4096 + nt * 128 + wc * 32 + fr * 2;
;           const float s0 = acc[ai][0][m][0][j] * sigm(acc[ai][0][m][1][j]);
;           const float s1 = acc[ai][1][m][0][j] * sigm(acc[ai][1][m][1][j]);
;           const unsigned at = *(const unsigned*)pr, ga = *(const unsigned*)(pr + 2048), gs = *(const unsigned*)(pr + 3072);
;           const float m0 = sigm(__uint_as_float(ga << 16)) * __uint_as_float(at << 16) + sigm(__uint_as_float(gs << 16)) * s0;
;           const float m1 = sigm(__uint_as_float(ga & 0xffff0000u)) * __uint_as_float(at & 0xffff0000u) +
;                            sigm(__uint_as_float(gs & 0xffff0000u)) * s1;
;           __builtin_nontemporal_store(pack2(m0, m1), (unsigned*)pr);
;         }
.LBB0_360:
	s_or_b64 exec, exec, s[2:3]
	s_mov_b32 s30, 0xbfb8aa3b
	s_mov_b32 s31, 0xbfb8aa3b
	s_mov_b32 s34, 1.0
	s_mov_b32 s35, 1.0
	v_lshlrev_b32_e32 v128, 6, v132
	v_lshl_add_u32 v128, v135, 2, v128
	v_lshlrev_b32_e32 v128, 13, v128
	s_lshl_b32 s2, s12, 8
	v_lshl_add_u32 v129, v133, 6, s2
	v_lshl_add_u32 v129, v134, 2, v129
	v_add_u32_e32 v137, v128, v129
	s_add_u32 s2, s64, 0x1000
	s_addc_u32 s3, s65, 0
	global_load_dword v138, v137, s[2:3] offset:-4096
	global_load_dword v140, v137, s[2:3]
	global_load_dword v142, v137, s[2:3] offset:2048
	s_add_u32 s2, s64, 0x3000
	s_addc_u32 s3, s65, 0
	global_load_dword v139, v137, s[2:3] offset:-4096
	global_load_dword v141, v137, s[2:3]
	global_load_dword v143, v137, s[2:3] offset:2048
	s_add_u32 s2, s64, 0x5000
	s_addc_u32 s3, s65, 0
	global_load_dword v144, v137, s[2:3] offset:-4096
	global_load_dword v146, v137, s[2:3]
	global_load_dword v148, v137, s[2:3] offset:2048
	s_add_u32 s2, s64, 0x7000
	s_addc_u32 s3, s65, 0
	global_load_dword v145, v137, s[2:3] offset:-4096
	global_load_dword v147, v137, s[2:3]
	global_load_dword v149, v137, s[2:3] offset:2048
	s_add_u32 s2, s64, 0x21000
	s_addc_u32 s3, s65, 0
	global_load_dword v150, v137, s[2:3] offset:-4096
	global_load_dword v152, v137, s[2:3]
	global_load_dword v154, v137, s[2:3] offset:2048
	s_add_u32 s2, s64, 0x23000
	s_addc_u32 s3, s65, 0
	global_load_dword v151, v137, s[2:3] offset:-4096
	global_load_dword v153, v137, s[2:3]
	global_load_dword v155, v137, s[2:3] offset:2048
	s_add_u32 s2, s64, 0x25000
	s_addc_u32 s3, s65, 0
	global_load_dword v156, v137, s[2:3] offset:-4096
	global_load_dword v158, v137, s[2:3]
	global_load_dword v160, v137, s[2:3] offset:2048
	s_add_u32 s2, s64, 0x27000
	s_addc_u32 s3, s65, 0
	global_load_dword v157, v137, s[2:3] offset:-4096
	global_load_dword v159, v137, s[2:3]
	global_load_dword v161, v137, s[2:3] offset:2048
	s_add_u32 s2, s64, 0x41000
	s_addc_u32 s3, s65, 0
	global_load_dword v162, v137, s[2:3] offset:-4096
	global_load_dword v164, v137, s[2:3]
	global_load_dword v166, v137, s[2:3] offset:2048
	s_add_u32 s2, s64, 0x43000
	s_addc_u32 s3, s65, 0
	global_load_dword v163, v137, s[2:3] offset:-4096
	global_load_dword v165, v137, s[2:3]
	global_load_dword v167, v137, s[2:3] offset:2048
	s_add_u32 s2, s64, 0x45000
	s_addc_u32 s3, s65, 0
	global_load_dword v168, v137, s[2:3] offset:-4096
	global_load_dword v170, v137, s[2:3]
	global_load_dword v172, v137, s[2:3] offset:2048
	s_add_u32 s2, s64, 0x47000
	s_addc_u32 s3, s65, 0
	global_load_dword v169, v137, s[2:3] offset:-4096
	global_load_dword v171, v137, s[2:3]
	global_load_dword v173, v137, s[2:3] offset:2048
	s_add_u32 s2, s64, 0x61000
	s_addc_u32 s3, s65, 0
	global_load_dword v174, v137, s[2:3] offset:-4096
	global_load_dword v176, v137, s[2:3]
	global_load_dword v178, v137, s[2:3] offset:2048
	s_add_u32 s2, s64, 0x63000
	s_addc_u32 s3, s65, 0
	global_load_dword v175, v137, s[2:3] offset:-4096
	global_load_dword v177, v137, s[2:3]
	global_load_dword v179, v137, s[2:3] offset:2048
	s_add_u32 s2, s64, 0x65000
	s_addc_u32 s3, s65, 0
	global_load_dword v180, v137, s[2:3] offset:-4096
	global_load_dword v182, v137, s[2:3]
	global_load_dword v184, v137, s[2:3] offset:2048
	s_add_u32 s2, s64, 0x67000
	s_addc_u32 s3, s65, 0
	global_load_dword v181, v137, s[2:3] offset:-4096
	global_load_dword v183, v137, s[2:3]
	global_load_dword v185, v137, s[2:3] offset:2048
	s_add_u32 s2, s64, 0x101000
	s_addc_u32 s3, s65, 0
	global_load_dword v186, v137, s[2:3] offset:-4096
	global_load_dword v188, v137, s[2:3]
	global_load_dword v190, v137, s[2:3] offset:2048
	s_add_u32 s2, s64, 0x103000
	s_addc_u32 s3, s65, 0
	global_load_dword v187, v137, s[2:3] offset:-4096
	global_load_dword v189, v137, s[2:3]
	global_load_dword v191, v137, s[2:3] offset:2048
	s_add_u32 s2, s64, 0x105000
	s_addc_u32 s3, s65, 0
	global_load_dword v192, v137, s[2:3] offset:-4096
	global_load_dword v194, v137, s[2:3]
	global_load_dword v196, v137, s[2:3] offset:2048
	s_add_u32 s2, s64, 0x107000
	s_addc_u32 s3, s65, 0
	global_load_dword v193, v137, s[2:3] offset:-4096
	global_load_dword v195, v137, s[2:3]
	global_load_dword v197, v137, s[2:3] offset:2048
	s_add_u32 s2, s64, 0x121000
	s_addc_u32 s3, s65, 0
	global_load_dword v198, v137, s[2:3] offset:-4096
	global_load_dword v200, v137, s[2:3]
	global_load_dword v202, v137, s[2:3] offset:2048
	s_add_u32 s2, s64, 0x123000
	s_addc_u32 s3, s65, 0
	global_load_dword v199, v137, s[2:3] offset:-4096
	global_load_dword v201, v137, s[2:3]
	global_load_dword v203, v137, s[2:3] offset:2048
	s_add_u32 s2, s64, 0x125000
	s_addc_u32 s3, s65, 0
	global_load_dword v204, v137, s[2:3] offset:-4096
	global_load_dword v206, v137, s[2:3]
	global_load_dword v208, v137, s[2:3] offset:2048
	s_add_u32 s2, s64, 0x127000
	s_addc_u32 s3, s65, 0
	global_load_dword v205, v137, s[2:3] offset:-4096
	global_load_dword v207, v137, s[2:3]
	global_load_dword v209, v137, s[2:3] offset:2048
	s_add_u32 s2, s64, 0x141000
	s_addc_u32 s3, s65, 0
	global_load_dword v210, v137, s[2:3] offset:-4096
	global_load_dword v212, v137, s[2:3]
	global_load_dword v214, v137, s[2:3] offset:2048
	s_add_u32 s2, s64, 0x143000
	s_addc_u32 s3, s65, 0
	global_load_dword v211, v137, s[2:3] offset:-4096
	global_load_dword v213, v137, s[2:3]
	global_load_dword v215, v137, s[2:3] offset:2048
	s_add_u32 s2, s64, 0x145000
	s_addc_u32 s3, s65, 0
	global_load_dword v216, v137, s[2:3] offset:-4096
	global_load_dword v218, v137, s[2:3]
	global_load_dword v220, v137, s[2:3] offset:2048
	s_add_u32 s2, s64, 0x147000
	s_addc_u32 s3, s65, 0
	global_load_dword v217, v137, s[2:3] offset:-4096
	global_load_dword v219, v137, s[2:3]
	global_load_dword v221, v137, s[2:3] offset:2048
	s_add_u32 s2, s64, 0x161000
	s_addc_u32 s3, s65, 0
	global_load_dword v222, v137, s[2:3] offset:-4096
	global_load_dword v224, v137, s[2:3]
	global_load_dword v226, v137, s[2:3] offset:2048
	s_add_u32 s2, s64, 0x163000
	s_addc_u32 s3, s65, 0
	global_load_dword v223, v137, s[2:3] offset:-4096
	global_load_dword v225, v137, s[2:3]
	global_load_dword v227, v137, s[2:3] offset:2048
	s_add_u32 s2, s64, 0x165000
	s_addc_u32 s3, s65, 0
	global_load_dword v228, v137, s[2:3] offset:-4096
	global_load_dword v230, v137, s[2:3]
	global_load_dword v232, v137, s[2:3] offset:2048
	s_add_u32 s2, s64, 0x167000
	s_addc_u32 s3, s65, 0
	global_load_dword v229, v137, s[2:3] offset:-4096
	global_load_dword v231, v137, s[2:3]
	global_load_dword v233, v137, s[2:3] offset:2048
	v_pk_mul_f32 v[234:235], v[120:121], s[30:31]
	v_pk_mul_f32 v[236:237], v[124:125], s[30:31]
	v_exp_f32_e32 v234, v234
	v_exp_f32_e32 v235, v235
	v_exp_f32_e32 v236, v236
	v_exp_f32_e32 v237, v237
	s_waitcnt vmcnt(63)
; __device__ __forceinline__ float sigm(float x) { return __builtin_amdgcn_rcpf(1.f + __expf(-x)); }
; __device__ __forceinline__ void gemm_glu_merge(u16* __restrict__ proj, const u16* __restrict__ Wt) {
;     ...
;           const int row = ai * 128 + wr * 64 + m * 16 + fq * 4 + j;
;           u16* pr = proj + (size_t)row * 4096 + nt * 128 + wc * 32 + fr * 2;
;           const float s0 = acc[ai][0][m][0][j] * sigm(acc[ai][0][m][1][j]);
;           const float s1 = acc[ai][1][m][0][j] * sigm(acc[ai][1][m][1][j]);
;           const unsigned at = *(const unsigned*)pr, ga = *(const unsigned*)(pr + 2048), gs = *(const unsigned*)(pr + 3072);
;           const float m0 = sigm(__uint_as_float(ga << 16)) * __uint_as_float(at << 16) + sigm(__uint_as_float(gs << 16)) * s0;
;           const float m1 = sigm(__uint_as_float(ga & 0xffff0000u)) * __uint_as_float(at & 0xffff0000u) +
;                            sigm(__uint_as_float(gs & 0xffff0000u)) * s1;
;           __builtin_nontemporal_store(pack2(m0, m1), (unsigned*)pr);
	v_lshlrev_b32_e32 v238, 16, v138
	v_lshlrev_b32_e32 v239, 16, v139
	v_lshlrev_b32_e32 v240, 16, v140
	v_lshlrev_b32_e32 v241, 16, v141
	v_lshlrev_b32_e32 v242, 16, v142
	v_lshlrev_b32_e32 v243, 16, v143
	v_and_b32_e32 v138, 0xffff0000, v138
	v_and_b32_e32 v139, 0xffff0000, v139
	v_and_b32_e32 v140, 0xffff0000, v140
	v_and_b32_e32 v141, 0xffff0000, v141
	v_and_b32_e32 v142, 0xffff0000, v142
	v_and_b32_e32 v143, 0xffff0000, v143
	v_pk_add_f32 v[234:235], v[234:235], s[34:35]
	v_pk_add_f32 v[236:237], v[236:237], s[34:35]
	v_pk_mul_f32 v[240:241], v[240:241], s[30:31]
	v_pk_mul_f32 v[140:141], v[140:141], s[30:31]
	v_pk_mul_f32 v[242:243], v[242:243], s[30:31]
	v_pk_mul_f32 v[142:143], v[142:143], s[30:31]
	v_rcp_f32_e32 v234, v234
	v_rcp_f32_e32 v235, v235
	v_rcp_f32_e32 v236, v236
	v_rcp_f32_e32 v237, v237
	v_exp_f32_e32 v240, v240
	v_exp_f32_e32 v241, v241
	v_exp_f32_e32 v140, v140
	v_exp_f32_e32 v141, v141
	v_exp_f32_e32 v242, v242
	v_exp_f32_e32 v243, v243
	v_exp_f32_e32 v142, v142
	v_exp_f32_e32 v143, v143
	v_pk_mul_f32 v[234:235], v[112:113], v[234:235]
	v_pk_mul_f32 v[236:237], v[116:117], v[236:237]
	v_pk_add_f32 v[240:241], v[240:241], s[34:35]
	v_pk_add_f32 v[140:141], v[140:141], s[34:35]
	v_pk_add_f32 v[242:243], v[242:243], s[34:35]
	v_pk_add_f32 v[142:143], v[142:143], s[34:35]
	v_rcp_f32_e32 v240, v240
	v_rcp_f32_e32 v241, v241
	v_rcp_f32_e32 v140, v140
	v_rcp_f32_e32 v141, v141
	v_rcp_f32_e32 v242, v242
	v_rcp_f32_e32 v243, v243
	v_rcp_f32_e32 v142, v142
	v_rcp_f32_e32 v143, v143
	v_pk_mul_f32 v[238:239], v[240:241], v[238:239]
	v_pk_mul_f32 v[138:139], v[140:141], v[138:139]
	v_pk_fma_f32 v[238:239], v[242:243], v[234:235], v[238:239]
	v_pk_fma_f32 v[138:139], v[142:143], v[236:237], v[138:139]
	v_cvt_pk_bf16_f32 v240, v238, v138
	v_cvt_pk_bf16_f32 v241, v239, v139
	s_add_u32 s2, s64, 0x1000
	s_addc_u32 s3, s65, 0
	global_store_dword v137, v240, s[2:3] offset:-4096 nt
	s_add_u32 s2, s64, 0x3000
	s_addc_u32 s3, s65, 0
	global_store_dword v137, v241, s[2:3] offset:-4096 nt
	v_pk_mul_f32 v[244:245], v[122:123], s[30:31]
	v_pk_mul_f32 v[246:247], v[126:127], s[30:31]
	v_exp_f32_e32 v244, v244
	v_exp_f32_e32 v245, v245
	v_exp_f32_e32 v246, v246
	v_exp_f32_e32 v247, v247
	s_waitcnt vmcnt(63)
	v_lshlrev_b32_e32 v248, 16, v144
	v_lshlrev_b32_e32 v249, 16, v145
	v_lshlrev_b32_e32 v250, 16, v146
	v_lshlrev_b32_e32 v251, 16, v147
	v_lshlrev_b32_e32 v252, 16, v148
	v_lshlrev_b32_e32 v253, 16, v149
	v_and_b32_e32 v144, 0xffff0000, v144
	v_and_b32_e32 v145, 0xffff0000, v145
	v_and_b32_e32 v146, 0xffff0000, v146
	v_and_b32_e32 v147, 0xffff0000, v147
	v_and_b32_e32 v148, 0xffff0000, v148
	v_and_b32_e32 v149, 0xffff0000, v149
	v_pk_add_f32 v[244:245], v[244:245], s[34:35]
	v_pk_add_f32 v[246:247], v[246:247], s[34:35]
	v_pk_mul_f32 v[250:251], v[250:251], s[30:31]
	v_pk_mul_f32 v[146:147], v[146:147], s[30:31]
	v_pk_mul_f32 v[252:253], v[252:253], s[30:31]
	v_pk_mul_f32 v[148:149], v[148:149], s[30:31]
	v_rcp_f32_e32 v244, v244
	v_rcp_f32_e32 v245, v245
	v_rcp_f32_e32 v246, v246
	v_rcp_f32_e32 v247, v247
	v_exp_f32_e32 v250, v250
	v_exp_f32_e32 v251, v251
	v_exp_f32_e32 v146, v146
	v_exp_f32_e32 v147, v147
	v_exp_f32_e32 v252, v252
	v_exp_f32_e32 v253, v253
	v_exp_f32_e32 v148, v148
	v_exp_f32_e32 v149, v149
	v_pk_mul_f32 v[244:245], v[114:115], v[244:245]
	v_pk_mul_f32 v[246:247], v[118:119], v[246:247]
	v_pk_add_f32 v[250:251], v[250:251], s[34:35]
	v_pk_add_f32 v[146:147], v[146:147], s[34:35]
	v_pk_add_f32 v[252:253], v[252:253], s[34:35]
	v_pk_add_f32 v[148:149], v[148:149], s[34:35]
	v_rcp_f32_e32 v250, v250
	v_rcp_f32_e32 v251, v251
	v_rcp_f32_e32 v146, v146
	v_rcp_f32_e32 v147, v147
	v_rcp_f32_e32 v252, v252
	v_rcp_f32_e32 v253, v253
	v_rcp_f32_e32 v148, v148
	v_rcp_f32_e32 v149, v149
	v_pk_mul_f32 v[248:249], v[250:251], v[248:249]
	v_pk_mul_f32 v[144:145], v[146:147], v[144:145]
	v_pk_fma_f32 v[248:249], v[252:253], v[244:245], v[248:249]
	v_pk_fma_f32 v[144:145], v[148:149], v[246:247], v[144:145]
	v_cvt_pk_bf16_f32 v250, v248, v144
	v_cvt_pk_bf16_f32 v251, v249, v145
	s_add_u32 s2, s64, 0x5000
	s_addc_u32 s3, s65, 0
	global_store_dword v137, v250, s[2:3] offset:-4096 nt
	s_add_u32 s2, s64, 0x7000
	s_addc_u32 s3, s65, 0
	global_store_dword v137, v251, s[2:3] offset:-4096 nt
	v_pk_mul_f32 v[234:235], v[104:105], s[30:31]
	v_pk_mul_f32 v[236:237], v[108:109], s[30:31]
	v_exp_f32_e32 v234, v234
	v_exp_f32_e32 v235, v235
	v_exp_f32_e32 v236, v236
	v_exp_f32_e32 v237, v237
	s_waitcnt vmcnt(63)
	v_lshlrev_b32_e32 v238, 16, v150
	v_lshlrev_b32_e32 v239, 16, v151
	v_lshlrev_b32_e32 v240, 16, v152
	v_lshlrev_b32_e32 v241, 16, v153
	v_lshlrev_b32_e32 v242, 16, v154
	v_lshlrev_b32_e32 v243, 16, v155
	v_and_b32_e32 v150, 0xffff0000, v150
	v_and_b32_e32 v151, 0xffff0000, v151
	v_and_b32_e32 v152, 0xffff0000, v152
	v_and_b32_e32 v153, 0xffff0000, v153
	v_and_b32_e32 v154, 0xffff0000, v154
	v_and_b32_e32 v155, 0xffff0000, v155
	v_pk_add_f32 v[234:235], v[234:235], s[34:35]
	v_pk_add_f32 v[236:237], v[236:237], s[34:35]
	v_pk_mul_f32 v[240:241], v[240:241], s[30:31]
	v_pk_mul_f32 v[152:153], v[152:153], s[30:31]
	v_pk_mul_f32 v[242:243], v[242:243], s[30:31]
	v_pk_mul_f32 v[154:155], v[154:155], s[30:31]
	v_rcp_f32_e32 v234, v234
	v_rcp_f32_e32 v235, v235
	v_rcp_f32_e32 v236, v236
	v_rcp_f32_e32 v237, v237
	v_exp_f32_e32 v240, v240
	v_exp_f32_e32 v241, v241
	v_exp_f32_e32 v152, v152
	v_exp_f32_e32 v153, v153
	v_exp_f32_e32 v242, v242
	v_exp_f32_e32 v243, v243
	v_exp_f32_e32 v154, v154
	v_exp_f32_e32 v155, v155
	v_pk_mul_f32 v[234:235], v[96:97], v[234:235]
	v_pk_mul_f32 v[236:237], v[100:101], v[236:237]
	v_pk_add_f32 v[240:241], v[240:241], s[34:35]
	v_pk_add_f32 v[152:153], v[152:153], s[34:35]
	v_pk_add_f32 v[242:243], v[242:243], s[34:35]
	v_pk_add_f32 v[154:155], v[154:155], s[34:35]
	v_rcp_f32_e32 v240, v240
	v_rcp_f32_e32 v241, v241
	v_rcp_f32_e32 v152, v152
	v_rcp_f32_e32 v153, v153
	v_rcp_f32_e32 v242, v242
	v_rcp_f32_e32 v243, v243
	v_rcp_f32_e32 v154, v154
	v_rcp_f32_e32 v155, v155
	v_pk_mul_f32 v[238:239], v[240:241], v[238:239]
	v_pk_mul_f32 v[150:151], v[152:153], v[150:151]
	v_pk_fma_f32 v[238:239], v[242:243], v[234:235], v[238:239]
	v_pk_fma_f32 v[150:151], v[154:155], v[236:237], v[150:151]
	v_cvt_pk_bf16_f32 v240, v238, v150
	v_cvt_pk_bf16_f32 v241, v239, v151
	s_add_u32 s2, s64, 0x21000
	s_addc_u32 s3, s65, 0
	global_store_dword v137, v240, s[2:3] offset:-4096 nt
	s_add_u32 s2, s64, 0x23000
	s_addc_u32 s3, s65, 0
	global_store_dword v137, v241, s[2:3] offset:-4096 nt
	v_pk_mul_f32 v[244:245], v[106:107], s[30:31]
	v_pk_mul_f32 v[246:247], v[110:111], s[30:31]
	v_exp_f32_e32 v244, v244
	v_exp_f32_e32 v245, v245
	v_exp_f32_e32 v246, v246
	v_exp_f32_e32 v247, v247
	s_waitcnt vmcnt(63)
; __device__ __forceinline__ float sigm(float x) { return __builtin_amdgcn_rcpf(1.f + __expf(-x)); }
; __device__ __forceinline__ void gemm_glu_merge(u16* __restrict__ proj, const u16* __restrict__ Wt) {
;     ...
;           const int row = ai * 128 + wr * 64 + m * 16 + fq * 4 + j;
;           u16* pr = proj + (size_t)row * 4096 + nt * 128 + wc * 32 + fr * 2;
;           const float s0 = acc[ai][0][m][0][j] * sigm(acc[ai][0][m][1][j]);
;           const float s1 = acc[ai][1][m][0][j] * sigm(acc[ai][1][m][1][j]);
;           const unsigned at = *(const unsigned*)pr, ga = *(const unsigned*)(pr + 2048), gs = *(const unsigned*)(pr + 3072);
;           const float m0 = sigm(__uint_as_float(ga << 16)) * __uint_as_float(at << 16) + sigm(__uint_as_float(gs << 16)) * s0;
;           const float m1 = sigm(__uint_as_float(ga & 0xffff0000u)) * __uint_as_float(at & 0xffff0000u) +
;                            sigm(__uint_as_float(gs & 0xffff0000u)) * s1;
;           __builtin_nontemporal_store(pack2(m0, m1), (unsigned*)pr);
	v_lshlrev_b32_e32 v248, 16, v156
	v_lshlrev_b32_e32 v249, 16, v157
	v_lshlrev_b32_e32 v250, 16, v158
	v_lshlrev_b32_e32 v251, 16, v159
	v_lshlrev_b32_e32 v252, 16, v160
	v_lshlrev_b32_e32 v253, 16, v161
	v_and_b32_e32 v156, 0xffff0000, v156
	v_and_b32_e32 v157, 0xffff0000, v157
	v_and_b32_e32 v158, 0xffff0000, v158
	v_and_b32_e32 v159, 0xffff0000, v159
	v_and_b32_e32 v160, 0xffff0000, v160
	v_and_b32_e32 v161, 0xffff0000, v161
	v_pk_add_f32 v[244:245], v[244:245], s[34:35]
	v_pk_add_f32 v[246:247], v[246:247], s[34:35]
	v_pk_mul_f32 v[250:251], v[250:251], s[30:31]
	v_pk_mul_f32 v[158:159], v[158:159], s[30:31]
	v_pk_mul_f32 v[252:253], v[252:253], s[30:31]
	v_pk_mul_f32 v[160:161], v[160:161], s[30:31]
	v_rcp_f32_e32 v244, v244
	v_rcp_f32_e32 v245, v245
	v_rcp_f32_e32 v246, v246
	v_rcp_f32_e32 v247, v247
	v_exp_f32_e32 v250, v250
	v_exp_f32_e32 v251, v251
	v_exp_f32_e32 v158, v158
	v_exp_f32_e32 v159, v159
	v_exp_f32_e32 v252, v252
	v_exp_f32_e32 v253, v253
	v_exp_f32_e32 v160, v160
	v_exp_f32_e32 v161, v161
	v_pk_mul_f32 v[244:245], v[98:99], v[244:245]
	v_pk_mul_f32 v[246:247], v[102:103], v[246:247]
	v_pk_add_f32 v[250:251], v[250:251], s[34:35]
	v_pk_add_f32 v[158:159], v[158:159], s[34:35]
	v_pk_add_f32 v[252:253], v[252:253], s[34:35]
	v_pk_add_f32 v[160:161], v[160:161], s[34:35]
	v_rcp_f32_e32 v250, v250
	v_rcp_f32_e32 v251, v251
	v_rcp_f32_e32 v158, v158
	v_rcp_f32_e32 v159, v159
	v_rcp_f32_e32 v252, v252
	v_rcp_f32_e32 v253, v253
	v_rcp_f32_e32 v160, v160
	v_rcp_f32_e32 v161, v161
	v_pk_mul_f32 v[248:249], v[250:251], v[248:249]
	v_pk_mul_f32 v[156:157], v[158:159], v[156:157]
	v_pk_fma_f32 v[248:249], v[252:253], v[244:245], v[248:249]
	v_pk_fma_f32 v[156:157], v[160:161], v[246:247], v[156:157]
	v_cvt_pk_bf16_f32 v250, v248, v156
	v_cvt_pk_bf16_f32 v251, v249, v157
	s_add_u32 s2, s64, 0x25000
	s_addc_u32 s3, s65, 0
	global_store_dword v137, v250, s[2:3] offset:-4096 nt
	s_add_u32 s2, s64, 0x27000
	s_addc_u32 s3, s65, 0
	global_store_dword v137, v251, s[2:3] offset:-4096 nt
	v_pk_mul_f32 v[234:235], v[88:89], s[30:31]
	v_pk_mul_f32 v[236:237], v[92:93], s[30:31]
	v_exp_f32_e32 v234, v234
	v_exp_f32_e32 v235, v235
	v_exp_f32_e32 v236, v236
	v_exp_f32_e32 v237, v237
	s_waitcnt vmcnt(63)
	v_lshlrev_b32_e32 v238, 16, v162
	v_lshlrev_b32_e32 v239, 16, v163
	v_lshlrev_b32_e32 v240, 16, v164
	v_lshlrev_b32_e32 v241, 16, v165
	v_lshlrev_b32_e32 v242, 16, v166
	v_lshlrev_b32_e32 v243, 16, v167
	v_and_b32_e32 v162, 0xffff0000, v162
	v_and_b32_e32 v163, 0xffff0000, v163
	v_and_b32_e32 v164, 0xffff0000, v164
	v_and_b32_e32 v165, 0xffff0000, v165
	v_and_b32_e32 v166, 0xffff0000, v166
	v_and_b32_e32 v167, 0xffff0000, v167
	v_pk_add_f32 v[234:235], v[234:235], s[34:35]
	v_pk_add_f32 v[236:237], v[236:237], s[34:35]
	v_pk_mul_f32 v[240:241], v[240:241], s[30:31]
	v_pk_mul_f32 v[164:165], v[164:165], s[30:31]
	v_pk_mul_f32 v[242:243], v[242:243], s[30:31]
	v_pk_mul_f32 v[166:167], v[166:167], s[30:31]
	v_rcp_f32_e32 v234, v234
	v_rcp_f32_e32 v235, v235
	v_rcp_f32_e32 v236, v236
	v_rcp_f32_e32 v237, v237
	v_exp_f32_e32 v240, v240
	v_exp_f32_e32 v241, v241
	v_exp_f32_e32 v164, v164
	v_exp_f32_e32 v165, v165
	v_exp_f32_e32 v242, v242
	v_exp_f32_e32 v243, v243
	v_exp_f32_e32 v166, v166
	v_exp_f32_e32 v167, v167
	v_pk_mul_f32 v[234:235], v[80:81], v[234:235]
	v_pk_mul_f32 v[236:237], v[84:85], v[236:237]
	v_pk_add_f32 v[240:241], v[240:241], s[34:35]
	v_pk_add_f32 v[164:165], v[164:165], s[34:35]
	v_pk_add_f32 v[242:243], v[242:243], s[34:35]
	v_pk_add_f32 v[166:167], v[166:167], s[34:35]
	v_rcp_f32_e32 v240, v240
	v_rcp_f32_e32 v241, v241
	v_rcp_f32_e32 v164, v164
	v_rcp_f32_e32 v165, v165
	v_rcp_f32_e32 v242, v242
	v_rcp_f32_e32 v243, v243
	v_rcp_f32_e32 v166, v166
	v_rcp_f32_e32 v167, v167
	v_pk_mul_f32 v[238:239], v[240:241], v[238:239]
	v_pk_mul_f32 v[162:163], v[164:165], v[162:163]
	v_pk_fma_f32 v[238:239], v[242:243], v[234:235], v[238:239]
	v_pk_fma_f32 v[162:163], v[166:167], v[236:237], v[162:163]
	v_cvt_pk_bf16_f32 v240, v238, v162
	v_cvt_pk_bf16_f32 v241, v239, v163
	s_add_u32 s2, s64, 0x41000
	s_addc_u32 s3, s65, 0
	global_store_dword v137, v240, s[2:3] offset:-4096 nt
	s_add_u32 s2, s64, 0x43000
	s_addc_u32 s3, s65, 0
	global_store_dword v137, v241, s[2:3] offset:-4096 nt
	v_pk_mul_f32 v[244:245], v[90:91], s[30:31]
	v_pk_mul_f32 v[246:247], v[94:95], s[30:31]
	v_exp_f32_e32 v244, v244
	v_exp_f32_e32 v245, v245
	v_exp_f32_e32 v246, v246
	v_exp_f32_e32 v247, v247
	s_waitcnt vmcnt(63)
	v_lshlrev_b32_e32 v248, 16, v168
	v_lshlrev_b32_e32 v249, 16, v169
	v_lshlrev_b32_e32 v250, 16, v170
	v_lshlrev_b32_e32 v251, 16, v171
	v_lshlrev_b32_e32 v252, 16, v172
	v_lshlrev_b32_e32 v253, 16, v173
	v_and_b32_e32 v168, 0xffff0000, v168
	v_and_b32_e32 v169, 0xffff0000, v169
	v_and_b32_e32 v170, 0xffff0000, v170
	v_and_b32_e32 v171, 0xffff0000, v171
	v_and_b32_e32 v172, 0xffff0000, v172
	v_and_b32_e32 v173, 0xffff0000, v173
	v_pk_add_f32 v[244:245], v[244:245], s[34:35]
	v_pk_add_f32 v[246:247], v[246:247], s[34:35]
	v_pk_mul_f32 v[250:251], v[250:251], s[30:31]
	v_pk_mul_f32 v[170:171], v[170:171], s[30:31]
	v_pk_mul_f32 v[252:253], v[252:253], s[30:31]
	v_pk_mul_f32 v[172:173], v[172:173], s[30:31]
	v_rcp_f32_e32 v244, v244
	v_rcp_f32_e32 v245, v245
	v_rcp_f32_e32 v246, v246
	v_rcp_f32_e32 v247, v247
	v_exp_f32_e32 v250, v250
	v_exp_f32_e32 v251, v251
	v_exp_f32_e32 v170, v170
	v_exp_f32_e32 v171, v171
	v_exp_f32_e32 v252, v252
	v_exp_f32_e32 v253, v253
	v_exp_f32_e32 v172, v172
	v_exp_f32_e32 v173, v173
	v_pk_mul_f32 v[244:245], v[82:83], v[244:245]
	v_pk_mul_f32 v[246:247], v[86:87], v[246:247]
	v_pk_add_f32 v[250:251], v[250:251], s[34:35]
	v_pk_add_f32 v[170:171], v[170:171], s[34:35]
	v_pk_add_f32 v[252:253], v[252:253], s[34:35]
	v_pk_add_f32 v[172:173], v[172:173], s[34:35]
	v_rcp_f32_e32 v250, v250
	v_rcp_f32_e32 v251, v251
	v_rcp_f32_e32 v170, v170
	v_rcp_f32_e32 v171, v171
	v_rcp_f32_e32 v252, v252
	v_rcp_f32_e32 v253, v253
	v_rcp_f32_e32 v172, v172
	v_rcp_f32_e32 v173, v173
	v_pk_mul_f32 v[248:249], v[250:251], v[248:249]
	v_pk_mul_f32 v[168:169], v[170:171], v[168:169]
	v_pk_fma_f32 v[248:249], v[252:253], v[244:245], v[248:249]
	v_pk_fma_f32 v[168:169], v[172:173], v[246:247], v[168:169]
	v_cvt_pk_bf16_f32 v250, v248, v168
	v_cvt_pk_bf16_f32 v251, v249, v169
	s_add_u32 s2, s64, 0x45000
	s_addc_u32 s3, s65, 0
	global_store_dword v137, v250, s[2:3] offset:-4096 nt
	s_add_u32 s2, s64, 0x47000
	s_addc_u32 s3, s65, 0
	global_store_dword v137, v251, s[2:3] offset:-4096 nt
	v_pk_mul_f32 v[234:235], v[72:73], s[30:31]
	v_pk_mul_f32 v[236:237], v[76:77], s[30:31]
	v_exp_f32_e32 v234, v234
	v_exp_f32_e32 v235, v235
	v_exp_f32_e32 v236, v236
	v_exp_f32_e32 v237, v237
	s_waitcnt vmcnt(63)
; __device__ __forceinline__ float sigm(float x) { return __builtin_amdgcn_rcpf(1.f + __expf(-x)); }
; __device__ __forceinline__ void gemm_glu_merge(u16* __restrict__ proj, const u16* __restrict__ Wt) {
;     ...
;           const int row = ai * 128 + wr * 64 + m * 16 + fq * 4 + j;
;           u16* pr = proj + (size_t)row * 4096 + nt * 128 + wc * 32 + fr * 2;
;           const float s0 = acc[ai][0][m][0][j] * sigm(acc[ai][0][m][1][j]);
;           const float s1 = acc[ai][1][m][0][j] * sigm(acc[ai][1][m][1][j]);
;           const unsigned at = *(const unsigned*)pr, ga = *(const unsigned*)(pr + 2048), gs = *(const unsigned*)(pr + 3072);
;           const float m0 = sigm(__uint_as_float(ga << 16)) * __uint_as_float(at << 16) + sigm(__uint_as_float(gs << 16)) * s0;
;           const float m1 = sigm(__uint_as_float(ga & 0xffff0000u)) * __uint_as_float(at & 0xffff0000u) +
;                            sigm(__uint_as_float(gs & 0xffff0000u)) * s1;
;           __builtin_nontemporal_store(pack2(m0, m1), (unsigned*)pr);
	v_lshlrev_b32_e32 v238, 16, v174
	v_lshlrev_b32_e32 v239, 16, v175
	v_lshlrev_b32_e32 v240, 16, v176
	v_lshlrev_b32_e32 v241, 16, v177
	v_lshlrev_b32_e32 v242, 16, v178
	v_lshlrev_b32_e32 v243, 16, v179
	v_and_b32_e32 v174, 0xffff0000, v174
	v_and_b32_e32 v175, 0xffff0000, v175
	v_and_b32_e32 v176, 0xffff0000, v176
	v_and_b32_e32 v177, 0xffff0000, v177
	v_and_b32_e32 v178, 0xffff0000, v178
	v_and_b32_e32 v179, 0xffff0000, v179
	v_pk_add_f32 v[234:235], v[234:235], s[34:35]
	v_pk_add_f32 v[236:237], v[236:237], s[34:35]
	v_pk_mul_f32 v[240:241], v[240:241], s[30:31]
	v_pk_mul_f32 v[176:177], v[176:177], s[30:31]
	v_pk_mul_f32 v[242:243], v[242:243], s[30:31]
	v_pk_mul_f32 v[178:179], v[178:179], s[30:31]
	v_rcp_f32_e32 v234, v234
	v_rcp_f32_e32 v235, v235
	v_rcp_f32_e32 v236, v236
	v_rcp_f32_e32 v237, v237
	v_exp_f32_e32 v240, v240
	v_exp_f32_e32 v241, v241
	v_exp_f32_e32 v176, v176
	v_exp_f32_e32 v177, v177
	v_exp_f32_e32 v242, v242
	v_exp_f32_e32 v243, v243
	v_exp_f32_e32 v178, v178
	v_exp_f32_e32 v179, v179
	v_pk_mul_f32 v[234:235], v[64:65], v[234:235]
	v_pk_mul_f32 v[236:237], v[68:69], v[236:237]
	v_pk_add_f32 v[240:241], v[240:241], s[34:35]
	v_pk_add_f32 v[176:177], v[176:177], s[34:35]
	v_pk_add_f32 v[242:243], v[242:243], s[34:35]
	v_pk_add_f32 v[178:179], v[178:179], s[34:35]
	v_rcp_f32_e32 v240, v240
	v_rcp_f32_e32 v241, v241
	v_rcp_f32_e32 v176, v176
	v_rcp_f32_e32 v177, v177
	v_rcp_f32_e32 v242, v242
	v_rcp_f32_e32 v243, v243
	v_rcp_f32_e32 v178, v178
	v_rcp_f32_e32 v179, v179
	v_pk_mul_f32 v[238:239], v[240:241], v[238:239]
	v_pk_mul_f32 v[174:175], v[176:177], v[174:175]
	v_pk_fma_f32 v[238:239], v[242:243], v[234:235], v[238:239]
	v_pk_fma_f32 v[174:175], v[178:179], v[236:237], v[174:175]
	v_cvt_pk_bf16_f32 v240, v238, v174
	v_cvt_pk_bf16_f32 v241, v239, v175
	s_add_u32 s2, s64, 0x61000
	s_addc_u32 s3, s65, 0
	global_store_dword v137, v240, s[2:3] offset:-4096 nt
	s_add_u32 s2, s64, 0x63000
	s_addc_u32 s3, s65, 0
	global_store_dword v137, v241, s[2:3] offset:-4096 nt
	v_pk_mul_f32 v[244:245], v[74:75], s[30:31]
	v_pk_mul_f32 v[246:247], v[78:79], s[30:31]
	v_exp_f32_e32 v244, v244
	v_exp_f32_e32 v245, v245
	v_exp_f32_e32 v246, v246
	v_exp_f32_e32 v247, v247
	s_waitcnt vmcnt(62)
	v_lshlrev_b32_e32 v248, 16, v180
	v_lshlrev_b32_e32 v249, 16, v181
	v_lshlrev_b32_e32 v250, 16, v182
	v_lshlrev_b32_e32 v251, 16, v183
	v_lshlrev_b32_e32 v252, 16, v184
	v_lshlrev_b32_e32 v253, 16, v185
	v_and_b32_e32 v180, 0xffff0000, v180
	v_and_b32_e32 v181, 0xffff0000, v181
	v_and_b32_e32 v182, 0xffff0000, v182
	v_and_b32_e32 v183, 0xffff0000, v183
	v_and_b32_e32 v184, 0xffff0000, v184
	v_and_b32_e32 v185, 0xffff0000, v185
	v_pk_add_f32 v[244:245], v[244:245], s[34:35]
	v_pk_add_f32 v[246:247], v[246:247], s[34:35]
	v_pk_mul_f32 v[250:251], v[250:251], s[30:31]
	v_pk_mul_f32 v[182:183], v[182:183], s[30:31]
	v_pk_mul_f32 v[252:253], v[252:253], s[30:31]
	v_pk_mul_f32 v[184:185], v[184:185], s[30:31]
	v_rcp_f32_e32 v244, v244
	v_rcp_f32_e32 v245, v245
	v_rcp_f32_e32 v246, v246
	v_rcp_f32_e32 v247, v247
	v_exp_f32_e32 v250, v250
	v_exp_f32_e32 v251, v251
	v_exp_f32_e32 v182, v182
	v_exp_f32_e32 v183, v183
	v_exp_f32_e32 v252, v252
	v_exp_f32_e32 v253, v253
	v_exp_f32_e32 v184, v184
	v_exp_f32_e32 v185, v185
	v_pk_mul_f32 v[244:245], v[66:67], v[244:245]
	v_pk_mul_f32 v[246:247], v[70:71], v[246:247]
	v_pk_add_f32 v[250:251], v[250:251], s[34:35]
	v_pk_add_f32 v[182:183], v[182:183], s[34:35]
	v_pk_add_f32 v[252:253], v[252:253], s[34:35]
	v_pk_add_f32 v[184:185], v[184:185], s[34:35]
	v_rcp_f32_e32 v250, v250
	v_rcp_f32_e32 v251, v251
	v_rcp_f32_e32 v182, v182
	v_rcp_f32_e32 v183, v183
	v_rcp_f32_e32 v252, v252
	v_rcp_f32_e32 v253, v253
	v_rcp_f32_e32 v184, v184
	v_rcp_f32_e32 v185, v185
	v_pk_mul_f32 v[248:249], v[250:251], v[248:249]
	v_pk_mul_f32 v[180:181], v[182:183], v[180:181]
	v_pk_fma_f32 v[248:249], v[252:253], v[244:245], v[248:249]
	v_pk_fma_f32 v[180:181], v[184:185], v[246:247], v[180:181]
	v_cvt_pk_bf16_f32 v250, v248, v180
	v_cvt_pk_bf16_f32 v251, v249, v181
	s_add_u32 s2, s64, 0x65000
	s_addc_u32 s3, s65, 0
	global_store_dword v137, v250, s[2:3] offset:-4096 nt
	s_add_u32 s2, s64, 0x67000
	s_addc_u32 s3, s65, 0
	global_store_dword v137, v251, s[2:3] offset:-4096 nt
	v_pk_mul_f32 v[234:235], v[56:57], s[30:31]
	v_pk_mul_f32 v[236:237], v[60:61], s[30:31]
	v_exp_f32_e32 v234, v234
	v_exp_f32_e32 v235, v235
	v_exp_f32_e32 v236, v236
	v_exp_f32_e32 v237, v237
	s_waitcnt vmcnt(58)
	v_lshlrev_b32_e32 v238, 16, v186
	v_lshlrev_b32_e32 v239, 16, v187
	v_lshlrev_b32_e32 v240, 16, v188
	v_lshlrev_b32_e32 v241, 16, v189
	v_lshlrev_b32_e32 v242, 16, v190
	v_lshlrev_b32_e32 v243, 16, v191
	v_and_b32_e32 v186, 0xffff0000, v186
	v_and_b32_e32 v187, 0xffff0000, v187
	v_and_b32_e32 v188, 0xffff0000, v188
	v_and_b32_e32 v189, 0xffff0000, v189
	v_and_b32_e32 v190, 0xffff0000, v190
	v_and_b32_e32 v191, 0xffff0000, v191
	v_pk_add_f32 v[234:235], v[234:235], s[34:35]
	v_pk_add_f32 v[236:237], v[236:237], s[34:35]
	v_pk_mul_f32 v[240:241], v[240:241], s[30:31]
	v_pk_mul_f32 v[188:189], v[188:189], s[30:31]
	v_pk_mul_f32 v[242:243], v[242:243], s[30:31]
	v_pk_mul_f32 v[190:191], v[190:191], s[30:31]
	v_rcp_f32_e32 v234, v234
	v_rcp_f32_e32 v235, v235
	v_rcp_f32_e32 v236, v236
	v_rcp_f32_e32 v237, v237
	v_exp_f32_e32 v240, v240
	v_exp_f32_e32 v241, v241
	v_exp_f32_e32 v188, v188
	v_exp_f32_e32 v189, v189
	v_exp_f32_e32 v242, v242
	v_exp_f32_e32 v243, v243
	v_exp_f32_e32 v190, v190
	v_exp_f32_e32 v191, v191
	v_pk_mul_f32 v[234:235], v[48:49], v[234:235]
	v_pk_mul_f32 v[236:237], v[52:53], v[236:237]
	v_pk_add_f32 v[240:241], v[240:241], s[34:35]
	v_pk_add_f32 v[188:189], v[188:189], s[34:35]
	v_pk_add_f32 v[242:243], v[242:243], s[34:35]
	v_pk_add_f32 v[190:191], v[190:191], s[34:35]
	v_rcp_f32_e32 v240, v240
	v_rcp_f32_e32 v241, v241
	v_rcp_f32_e32 v188, v188
	v_rcp_f32_e32 v189, v189
	v_rcp_f32_e32 v242, v242
	v_rcp_f32_e32 v243, v243
	v_rcp_f32_e32 v190, v190
	v_rcp_f32_e32 v191, v191
	v_pk_mul_f32 v[238:239], v[240:241], v[238:239]
	v_pk_mul_f32 v[186:187], v[188:189], v[186:187]
	v_pk_fma_f32 v[238:239], v[242:243], v[234:235], v[238:239]
	v_pk_fma_f32 v[186:187], v[190:191], v[236:237], v[186:187]
	v_cvt_pk_bf16_f32 v240, v238, v186
	v_cvt_pk_bf16_f32 v241, v239, v187
	s_add_u32 s2, s64, 0x101000
	s_addc_u32 s3, s65, 0
	global_store_dword v137, v240, s[2:3] offset:-4096 nt
	s_add_u32 s2, s64, 0x103000
	s_addc_u32 s3, s65, 0
	global_store_dword v137, v241, s[2:3] offset:-4096 nt
	v_pk_mul_f32 v[244:245], v[58:59], s[30:31]
	v_pk_mul_f32 v[246:247], v[62:63], s[30:31]
	v_exp_f32_e32 v244, v244
	v_exp_f32_e32 v245, v245
	v_exp_f32_e32 v246, v246
	v_exp_f32_e32 v247, v247
	s_waitcnt vmcnt(54)
; __device__ __forceinline__ float sigm(float x) { return __builtin_amdgcn_rcpf(1.f + __expf(-x)); }
; __device__ __forceinline__ void gemm_glu_merge(u16* __restrict__ proj, const u16* __restrict__ Wt) {
;     ...
;           const int row = ai * 128 + wr * 64 + m * 16 + fq * 4 + j;
;           u16* pr = proj + (size_t)row * 4096 + nt * 128 + wc * 32 + fr * 2;
;           const float s0 = acc[ai][0][m][0][j] * sigm(acc[ai][0][m][1][j]);
;           const float s1 = acc[ai][1][m][0][j] * sigm(acc[ai][1][m][1][j]);
;           const unsigned at = *(const unsigned*)pr, ga = *(const unsigned*)(pr + 2048), gs = *(const unsigned*)(pr + 3072);
;           const float m0 = sigm(__uint_as_float(ga << 16)) * __uint_as_float(at << 16) + sigm(__uint_as_float(gs << 16)) * s0;
;           const float m1 = sigm(__uint_as_float(ga & 0xffff0000u)) * __uint_as_float(at & 0xffff0000u) +
;                            sigm(__uint_as_float(gs & 0xffff0000u)) * s1;
;           __builtin_nontemporal_store(pack2(m0, m1), (unsigned*)pr);
	v_lshlrev_b32_e32 v248, 16, v192
	v_lshlrev_b32_e32 v249, 16, v193
	v_lshlrev_b32_e32 v250, 16, v194
	v_lshlrev_b32_e32 v251, 16, v195
	v_lshlrev_b32_e32 v252, 16, v196
	v_lshlrev_b32_e32 v253, 16, v197
	v_and_b32_e32 v192, 0xffff0000, v192
	v_and_b32_e32 v193, 0xffff0000, v193
	v_and_b32_e32 v194, 0xffff0000, v194
	v_and_b32_e32 v195, 0xffff0000, v195
	v_and_b32_e32 v196, 0xffff0000, v196
	v_and_b32_e32 v197, 0xffff0000, v197
	v_pk_add_f32 v[244:245], v[244:245], s[34:35]
	v_pk_add_f32 v[246:247], v[246:247], s[34:35]
	v_pk_mul_f32 v[250:251], v[250:251], s[30:31]
	v_pk_mul_f32 v[194:195], v[194:195], s[30:31]
	v_pk_mul_f32 v[252:253], v[252:253], s[30:31]
	v_pk_mul_f32 v[196:197], v[196:197], s[30:31]
	v_rcp_f32_e32 v244, v244
	v_rcp_f32_e32 v245, v245
	v_rcp_f32_e32 v246, v246
	v_rcp_f32_e32 v247, v247
	v_exp_f32_e32 v250, v250
	v_exp_f32_e32 v251, v251
	v_exp_f32_e32 v194, v194
	v_exp_f32_e32 v195, v195
	v_exp_f32_e32 v252, v252
	v_exp_f32_e32 v253, v253
	v_exp_f32_e32 v196, v196
	v_exp_f32_e32 v197, v197
	v_pk_mul_f32 v[244:245], v[50:51], v[244:245]
	v_pk_mul_f32 v[246:247], v[54:55], v[246:247]
	v_pk_add_f32 v[250:251], v[250:251], s[34:35]
	v_pk_add_f32 v[194:195], v[194:195], s[34:35]
	v_pk_add_f32 v[252:253], v[252:253], s[34:35]
	v_pk_add_f32 v[196:197], v[196:197], s[34:35]
	v_rcp_f32_e32 v250, v250
	v_rcp_f32_e32 v251, v251
	v_rcp_f32_e32 v194, v194
	v_rcp_f32_e32 v195, v195
	v_rcp_f32_e32 v252, v252
	v_rcp_f32_e32 v253, v253
	v_rcp_f32_e32 v196, v196
	v_rcp_f32_e32 v197, v197
	v_pk_mul_f32 v[248:249], v[250:251], v[248:249]
	v_pk_mul_f32 v[192:193], v[194:195], v[192:193]
	v_pk_fma_f32 v[248:249], v[252:253], v[244:245], v[248:249]
	v_pk_fma_f32 v[192:193], v[196:197], v[246:247], v[192:193]
	v_cvt_pk_bf16_f32 v250, v248, v192
	v_cvt_pk_bf16_f32 v251, v249, v193
	s_add_u32 s2, s64, 0x105000
	s_addc_u32 s3, s65, 0
	global_store_dword v137, v250, s[2:3] offset:-4096 nt
	s_add_u32 s2, s64, 0x107000
	s_addc_u32 s3, s65, 0
	global_store_dword v137, v251, s[2:3] offset:-4096 nt
	v_pk_mul_f32 v[234:235], v[40:41], s[30:31]
	v_pk_mul_f32 v[236:237], v[44:45], s[30:31]
	v_exp_f32_e32 v234, v234
	v_exp_f32_e32 v235, v235
	v_exp_f32_e32 v236, v236
	v_exp_f32_e32 v237, v237
	s_waitcnt vmcnt(50)
	v_lshlrev_b32_e32 v238, 16, v198
	v_lshlrev_b32_e32 v239, 16, v199
	v_lshlrev_b32_e32 v240, 16, v200
	v_lshlrev_b32_e32 v241, 16, v201
	v_lshlrev_b32_e32 v242, 16, v202
	v_lshlrev_b32_e32 v243, 16, v203
	v_and_b32_e32 v198, 0xffff0000, v198
	v_and_b32_e32 v199, 0xffff0000, v199
	v_and_b32_e32 v200, 0xffff0000, v200
	v_and_b32_e32 v201, 0xffff0000, v201
	v_and_b32_e32 v202, 0xffff0000, v202
	v_and_b32_e32 v203, 0xffff0000, v203
	v_pk_add_f32 v[234:235], v[234:235], s[34:35]
	v_pk_add_f32 v[236:237], v[236:237], s[34:35]
	v_pk_mul_f32 v[240:241], v[240:241], s[30:31]
	v_pk_mul_f32 v[200:201], v[200:201], s[30:31]
	v_pk_mul_f32 v[242:243], v[242:243], s[30:31]
	v_pk_mul_f32 v[202:203], v[202:203], s[30:31]
	v_rcp_f32_e32 v234, v234
	v_rcp_f32_e32 v235, v235
	v_rcp_f32_e32 v236, v236
	v_rcp_f32_e32 v237, v237
	v_exp_f32_e32 v240, v240
	v_exp_f32_e32 v241, v241
	v_exp_f32_e32 v200, v200
	v_exp_f32_e32 v201, v201
	v_exp_f32_e32 v242, v242
	v_exp_f32_e32 v243, v243
	v_exp_f32_e32 v202, v202
	v_exp_f32_e32 v203, v203
	v_pk_mul_f32 v[234:235], v[32:33], v[234:235]
	v_pk_mul_f32 v[236:237], v[36:37], v[236:237]
	v_pk_add_f32 v[240:241], v[240:241], s[34:35]
	v_pk_add_f32 v[200:201], v[200:201], s[34:35]
	v_pk_add_f32 v[242:243], v[242:243], s[34:35]
	v_pk_add_f32 v[202:203], v[202:203], s[34:35]
	v_rcp_f32_e32 v240, v240
	v_rcp_f32_e32 v241, v241
	v_rcp_f32_e32 v200, v200
	v_rcp_f32_e32 v201, v201
	v_rcp_f32_e32 v242, v242
	v_rcp_f32_e32 v243, v243
	v_rcp_f32_e32 v202, v202
	v_rcp_f32_e32 v203, v203
	v_pk_mul_f32 v[238:239], v[240:241], v[238:239]
	v_pk_mul_f32 v[198:199], v[200:201], v[198:199]
	v_pk_fma_f32 v[238:239], v[242:243], v[234:235], v[238:239]
	v_pk_fma_f32 v[198:199], v[202:203], v[236:237], v[198:199]
	v_cvt_pk_bf16_f32 v240, v238, v198
	v_cvt_pk_bf16_f32 v241, v239, v199
	s_add_u32 s2, s64, 0x121000
	s_addc_u32 s3, s65, 0
	global_store_dword v137, v240, s[2:3] offset:-4096 nt
	s_add_u32 s2, s64, 0x123000
	s_addc_u32 s3, s65, 0
	global_store_dword v137, v241, s[2:3] offset:-4096 nt
	v_pk_mul_f32 v[244:245], v[42:43], s[30:31]
	v_pk_mul_f32 v[246:247], v[46:47], s[30:31]
	v_exp_f32_e32 v244, v244
	v_exp_f32_e32 v245, v245
	v_exp_f32_e32 v246, v246
	v_exp_f32_e32 v247, v247
	s_waitcnt vmcnt(46)
	v_lshlrev_b32_e32 v248, 16, v204
	v_lshlrev_b32_e32 v249, 16, v205
	v_lshlrev_b32_e32 v250, 16, v206
	v_lshlrev_b32_e32 v251, 16, v207
	v_lshlrev_b32_e32 v252, 16, v208
	v_lshlrev_b32_e32 v253, 16, v209
	v_and_b32_e32 v204, 0xffff0000, v204
	v_and_b32_e32 v205, 0xffff0000, v205
	v_and_b32_e32 v206, 0xffff0000, v206
	v_and_b32_e32 v207, 0xffff0000, v207
	v_and_b32_e32 v208, 0xffff0000, v208
	v_and_b32_e32 v209, 0xffff0000, v209
	v_pk_add_f32 v[244:245], v[244:245], s[34:35]
	v_pk_add_f32 v[246:247], v[246:247], s[34:35]
	v_pk_mul_f32 v[250:251], v[250:251], s[30:31]
	v_pk_mul_f32 v[206:207], v[206:207], s[30:31]
	v_pk_mul_f32 v[252:253], v[252:253], s[30:31]
	v_pk_mul_f32 v[208:209], v[208:209], s[30:31]
	v_rcp_f32_e32 v244, v244
	v_rcp_f32_e32 v245, v245
	v_rcp_f32_e32 v246, v246
	v_rcp_f32_e32 v247, v247
	v_exp_f32_e32 v250, v250
	v_exp_f32_e32 v251, v251
	v_exp_f32_e32 v206, v206
	v_exp_f32_e32 v207, v207
	v_exp_f32_e32 v252, v252
	v_exp_f32_e32 v253, v253
	v_exp_f32_e32 v208, v208
	v_exp_f32_e32 v209, v209
	v_pk_mul_f32 v[244:245], v[34:35], v[244:245]
	v_pk_mul_f32 v[246:247], v[38:39], v[246:247]
	v_pk_add_f32 v[250:251], v[250:251], s[34:35]
	v_pk_add_f32 v[206:207], v[206:207], s[34:35]
	v_pk_add_f32 v[252:253], v[252:253], s[34:35]
	v_pk_add_f32 v[208:209], v[208:209], s[34:35]
	v_rcp_f32_e32 v250, v250
	v_rcp_f32_e32 v251, v251
	v_rcp_f32_e32 v206, v206
	v_rcp_f32_e32 v207, v207
	v_rcp_f32_e32 v252, v252
	v_rcp_f32_e32 v253, v253
	v_rcp_f32_e32 v208, v208
	v_rcp_f32_e32 v209, v209
	v_pk_mul_f32 v[248:249], v[250:251], v[248:249]
	v_pk_mul_f32 v[204:205], v[206:207], v[204:205]
	v_pk_fma_f32 v[248:249], v[252:253], v[244:245], v[248:249]
	v_pk_fma_f32 v[204:205], v[208:209], v[246:247], v[204:205]
	v_cvt_pk_bf16_f32 v250, v248, v204
	v_cvt_pk_bf16_f32 v251, v249, v205
	s_add_u32 s2, s64, 0x125000
	s_addc_u32 s3, s65, 0
	global_store_dword v137, v250, s[2:3] offset:-4096 nt
	s_add_u32 s2, s64, 0x127000
	s_addc_u32 s3, s65, 0
	global_store_dword v137, v251, s[2:3] offset:-4096 nt
	v_pk_mul_f32 v[234:235], v[24:25], s[30:31]
	v_pk_mul_f32 v[236:237], v[28:29], s[30:31]
	v_exp_f32_e32 v234, v234
	v_exp_f32_e32 v235, v235
	v_exp_f32_e32 v236, v236
	v_exp_f32_e32 v237, v237
	s_waitcnt vmcnt(42)
; __device__ __forceinline__ float sigm(float x) { return __builtin_amdgcn_rcpf(1.f + __expf(-x)); }
; __device__ __forceinline__ void gemm_glu_merge(u16* __restrict__ proj, const u16* __restrict__ Wt) {
;     ...
;           const int row = ai * 128 + wr * 64 + m * 16 + fq * 4 + j;
;           u16* pr = proj + (size_t)row * 4096 + nt * 128 + wc * 32 + fr * 2;
;           const float s0 = acc[ai][0][m][0][j] * sigm(acc[ai][0][m][1][j]);
;           const float s1 = acc[ai][1][m][0][j] * sigm(acc[ai][1][m][1][j]);
;           const unsigned at = *(const unsigned*)pr, ga = *(const unsigned*)(pr + 2048), gs = *(const unsigned*)(pr + 3072);
;           const float m0 = sigm(__uint_as_float(ga << 16)) * __uint_as_float(at << 16) + sigm(__uint_as_float(gs << 16)) * s0;
;           const float m1 = sigm(__uint_as_float(ga & 0xffff0000u)) * __uint_as_float(at & 0xffff0000u) +
;                            sigm(__uint_as_float(gs & 0xffff0000u)) * s1;
;           __builtin_nontemporal_store(pack2(m0, m1), (unsigned*)pr);
	v_lshlrev_b32_e32 v238, 16, v210
	v_lshlrev_b32_e32 v239, 16, v211
	v_lshlrev_b32_e32 v240, 16, v212
	v_lshlrev_b32_e32 v241, 16, v213
	v_lshlrev_b32_e32 v242, 16, v214
	v_lshlrev_b32_e32 v243, 16, v215
	v_and_b32_e32 v210, 0xffff0000, v210
	v_and_b32_e32 v211, 0xffff0000, v211
	v_and_b32_e32 v212, 0xffff0000, v212
	v_and_b32_e32 v213, 0xffff0000, v213
	v_and_b32_e32 v214, 0xffff0000, v214
	v_and_b32_e32 v215, 0xffff0000, v215
	v_pk_add_f32 v[234:235], v[234:235], s[34:35]
	v_pk_add_f32 v[236:237], v[236:237], s[34:35]
	v_pk_mul_f32 v[240:241], v[240:241], s[30:31]
	v_pk_mul_f32 v[212:213], v[212:213], s[30:31]
	v_pk_mul_f32 v[242:243], v[242:243], s[30:31]
	v_pk_mul_f32 v[214:215], v[214:215], s[30:31]
	v_rcp_f32_e32 v234, v234
	v_rcp_f32_e32 v235, v235
	v_rcp_f32_e32 v236, v236
	v_rcp_f32_e32 v237, v237
	v_exp_f32_e32 v240, v240
	v_exp_f32_e32 v241, v241
	v_exp_f32_e32 v212, v212
	v_exp_f32_e32 v213, v213
	v_exp_f32_e32 v242, v242
	v_exp_f32_e32 v243, v243
	v_exp_f32_e32 v214, v214
	v_exp_f32_e32 v215, v215
	v_pk_mul_f32 v[234:235], v[16:17], v[234:235]
	v_pk_mul_f32 v[236:237], v[20:21], v[236:237]
	v_pk_add_f32 v[240:241], v[240:241], s[34:35]
	v_pk_add_f32 v[212:213], v[212:213], s[34:35]
	v_pk_add_f32 v[242:243], v[242:243], s[34:35]
	v_pk_add_f32 v[214:215], v[214:215], s[34:35]
	v_rcp_f32_e32 v240, v240
	v_rcp_f32_e32 v241, v241
	v_rcp_f32_e32 v212, v212
	v_rcp_f32_e32 v213, v213
	v_rcp_f32_e32 v242, v242
	v_rcp_f32_e32 v243, v243
	v_rcp_f32_e32 v214, v214
	v_rcp_f32_e32 v215, v215
	v_pk_mul_f32 v[238:239], v[240:241], v[238:239]
	v_pk_mul_f32 v[210:211], v[212:213], v[210:211]
	v_pk_fma_f32 v[238:239], v[242:243], v[234:235], v[238:239]
	v_pk_fma_f32 v[210:211], v[214:215], v[236:237], v[210:211]
	v_cvt_pk_bf16_f32 v240, v238, v210
	v_cvt_pk_bf16_f32 v241, v239, v211
	s_add_u32 s2, s64, 0x141000
	s_addc_u32 s3, s65, 0
	global_store_dword v137, v240, s[2:3] offset:-4096 nt
	s_add_u32 s2, s64, 0x143000
	s_addc_u32 s3, s65, 0
	global_store_dword v137, v241, s[2:3] offset:-4096 nt
	v_pk_mul_f32 v[244:245], v[26:27], s[30:31]
	v_pk_mul_f32 v[246:247], v[30:31], s[30:31]
	v_exp_f32_e32 v244, v244
	v_exp_f32_e32 v245, v245
	v_exp_f32_e32 v246, v246
	v_exp_f32_e32 v247, v247
	s_waitcnt vmcnt(38)
	v_lshlrev_b32_e32 v248, 16, v216
	v_lshlrev_b32_e32 v249, 16, v217
	v_lshlrev_b32_e32 v250, 16, v218
	v_lshlrev_b32_e32 v251, 16, v219
	v_lshlrev_b32_e32 v252, 16, v220
	v_lshlrev_b32_e32 v253, 16, v221
	v_and_b32_e32 v216, 0xffff0000, v216
	v_and_b32_e32 v217, 0xffff0000, v217
	v_and_b32_e32 v218, 0xffff0000, v218
	v_and_b32_e32 v219, 0xffff0000, v219
	v_and_b32_e32 v220, 0xffff0000, v220
	v_and_b32_e32 v221, 0xffff0000, v221
	v_pk_add_f32 v[244:245], v[244:245], s[34:35]
	v_pk_add_f32 v[246:247], v[246:247], s[34:35]
	v_pk_mul_f32 v[250:251], v[250:251], s[30:31]
	v_pk_mul_f32 v[218:219], v[218:219], s[30:31]
	v_pk_mul_f32 v[252:253], v[252:253], s[30:31]
	v_pk_mul_f32 v[220:221], v[220:221], s[30:31]
	v_rcp_f32_e32 v244, v244
	v_rcp_f32_e32 v245, v245
	v_rcp_f32_e32 v246, v246
	v_rcp_f32_e32 v247, v247
	v_exp_f32_e32 v250, v250
	v_exp_f32_e32 v251, v251
	v_exp_f32_e32 v218, v218
	v_exp_f32_e32 v219, v219
	v_exp_f32_e32 v252, v252
	v_exp_f32_e32 v253, v253
	v_exp_f32_e32 v220, v220
	v_exp_f32_e32 v221, v221
	v_pk_mul_f32 v[244:245], v[18:19], v[244:245]
	v_pk_mul_f32 v[246:247], v[22:23], v[246:247]
	v_pk_add_f32 v[250:251], v[250:251], s[34:35]
	v_pk_add_f32 v[218:219], v[218:219], s[34:35]
	v_pk_add_f32 v[252:253], v[252:253], s[34:35]
	v_pk_add_f32 v[220:221], v[220:221], s[34:35]
	v_rcp_f32_e32 v250, v250
	v_rcp_f32_e32 v251, v251
	v_rcp_f32_e32 v218, v218
	v_rcp_f32_e32 v219, v219
	v_rcp_f32_e32 v252, v252
	v_rcp_f32_e32 v253, v253
	v_rcp_f32_e32 v220, v220
	v_rcp_f32_e32 v221, v221
	v_pk_mul_f32 v[248:249], v[250:251], v[248:249]
	v_pk_mul_f32 v[216:217], v[218:219], v[216:217]
	v_pk_fma_f32 v[248:249], v[252:253], v[244:245], v[248:249]
	v_pk_fma_f32 v[216:217], v[220:221], v[246:247], v[216:217]
	v_cvt_pk_bf16_f32 v250, v248, v216
	v_cvt_pk_bf16_f32 v251, v249, v217
	s_add_u32 s2, s64, 0x145000
	s_addc_u32 s3, s65, 0
	global_store_dword v137, v250, s[2:3] offset:-4096 nt
	s_add_u32 s2, s64, 0x147000
	s_addc_u32 s3, s65, 0
	global_store_dword v137, v251, s[2:3] offset:-4096 nt
	v_pk_mul_f32 v[234:235], v[8:9], s[30:31]
	v_pk_mul_f32 v[236:237], v[12:13], s[30:31]
	v_exp_f32_e32 v234, v234
	v_exp_f32_e32 v235, v235
	v_exp_f32_e32 v236, v236
	v_exp_f32_e32 v237, v237
	s_waitcnt vmcnt(34)
; __device__ __forceinline__ float sigm(float x) { return __builtin_amdgcn_rcpf(1.f + __expf(-x)); }
; __device__ __forceinline__ void gemm_glu_merge(u16* __restrict__ proj, const u16* __restrict__ Wt) {
;     ...
;   for (int nt = 0; nt < 8; ++nt) {
;     ...
;           const int row = ai * 128 + wr * 64 + m * 16 + fq * 4 + j;
;           u16* pr = proj + (size_t)row * 4096 + nt * 128 + wc * 32 + fr * 2;
;           const float s0 = acc[ai][0][m][0][j] * sigm(acc[ai][0][m][1][j]);
;           const float s1 = acc[ai][1][m][0][j] * sigm(acc[ai][1][m][1][j]);
;           const unsigned at = *(const unsigned*)pr, ga = *(const unsigned*)(pr + 2048), gs = *(const unsigned*)(pr + 3072);
;           const float m0 = sigm(__uint_as_float(ga << 16)) * __uint_as_float(at << 16) + sigm(__uint_as_float(gs << 16)) * s0;
;           const float m1 = sigm(__uint_as_float(ga & 0xffff0000u)) * __uint_as_float(at & 0xffff0000u) +
;                            sigm(__uint_as_float(gs & 0xffff0000u)) * s1;
;           __builtin_nontemporal_store(pack2(m0, m1), (unsigned*)pr);
;         }
	v_lshlrev_b32_e32 v238, 16, v222
	v_lshlrev_b32_e32 v239, 16, v223
	v_lshlrev_b32_e32 v240, 16, v224
	v_lshlrev_b32_e32 v241, 16, v225
	v_lshlrev_b32_e32 v242, 16, v226
	v_lshlrev_b32_e32 v243, 16, v227
	v_and_b32_e32 v222, 0xffff0000, v222
	v_and_b32_e32 v223, 0xffff0000, v223
	v_and_b32_e32 v224, 0xffff0000, v224
	v_and_b32_e32 v225, 0xffff0000, v225
	v_and_b32_e32 v226, 0xffff0000, v226
	v_and_b32_e32 v227, 0xffff0000, v227
	v_pk_add_f32 v[234:235], v[234:235], s[34:35]
	v_pk_add_f32 v[236:237], v[236:237], s[34:35]
	v_pk_mul_f32 v[240:241], v[240:241], s[30:31]
	v_pk_mul_f32 v[224:225], v[224:225], s[30:31]
	v_pk_mul_f32 v[242:243], v[242:243], s[30:31]
	v_pk_mul_f32 v[226:227], v[226:227], s[30:31]
	v_rcp_f32_e32 v234, v234
	v_rcp_f32_e32 v235, v235
	v_rcp_f32_e32 v236, v236
	v_rcp_f32_e32 v237, v237
	v_exp_f32_e32 v240, v240
	v_exp_f32_e32 v241, v241
	v_exp_f32_e32 v224, v224
	v_exp_f32_e32 v225, v225
	v_exp_f32_e32 v242, v242
	v_exp_f32_e32 v243, v243
	v_exp_f32_e32 v226, v226
	v_exp_f32_e32 v227, v227
	v_pk_mul_f32 v[234:235], v[0:1], v[234:235]
	v_pk_mul_f32 v[236:237], v[4:5], v[236:237]
	v_pk_add_f32 v[240:241], v[240:241], s[34:35]
	v_pk_add_f32 v[224:225], v[224:225], s[34:35]
	v_pk_add_f32 v[242:243], v[242:243], s[34:35]
	v_pk_add_f32 v[226:227], v[226:227], s[34:35]
	v_rcp_f32_e32 v240, v240
	v_rcp_f32_e32 v241, v241
	v_rcp_f32_e32 v224, v224
	v_rcp_f32_e32 v225, v225
	v_rcp_f32_e32 v242, v242
	v_rcp_f32_e32 v243, v243
	v_rcp_f32_e32 v226, v226
	v_rcp_f32_e32 v227, v227
	v_pk_mul_f32 v[238:239], v[240:241], v[238:239]
	v_pk_mul_f32 v[222:223], v[224:225], v[222:223]
	v_pk_fma_f32 v[238:239], v[242:243], v[234:235], v[238:239]
	v_pk_fma_f32 v[222:223], v[226:227], v[236:237], v[222:223]
	v_cvt_pk_bf16_f32 v240, v238, v222
	v_cvt_pk_bf16_f32 v241, v239, v223
	s_add_u32 s2, s64, 0x161000
	s_addc_u32 s3, s65, 0
	global_store_dword v137, v240, s[2:3] offset:-4096 nt
	s_add_u32 s2, s64, 0x163000
	s_addc_u32 s3, s65, 0
	global_store_dword v137, v241, s[2:3] offset:-4096 nt
	v_pk_mul_f32 v[244:245], v[10:11], s[30:31]
	v_pk_mul_f32 v[246:247], v[14:15], s[30:31]
	v_exp_f32_e32 v244, v244
	v_exp_f32_e32 v245, v245
	v_exp_f32_e32 v246, v246
	v_exp_f32_e32 v247, v247
	s_waitcnt vmcnt(30)
	v_lshlrev_b32_e32 v248, 16, v228
	v_lshlrev_b32_e32 v249, 16, v229
	v_lshlrev_b32_e32 v250, 16, v230
	v_lshlrev_b32_e32 v251, 16, v231
	v_lshlrev_b32_e32 v252, 16, v232
	v_lshlrev_b32_e32 v253, 16, v233
	v_and_b32_e32 v228, 0xffff0000, v228
	v_and_b32_e32 v229, 0xffff0000, v229
	v_and_b32_e32 v230, 0xffff0000, v230
	v_and_b32_e32 v231, 0xffff0000, v231
	v_and_b32_e32 v232, 0xffff0000, v232
	v_and_b32_e32 v233, 0xffff0000, v233
	v_pk_add_f32 v[244:245], v[244:245], s[34:35]
	v_pk_add_f32 v[246:247], v[246:247], s[34:35]
	v_pk_mul_f32 v[250:251], v[250:251], s[30:31]
	v_pk_mul_f32 v[230:231], v[230:231], s[30:31]
	v_pk_mul_f32 v[252:253], v[252:253], s[30:31]
	v_pk_mul_f32 v[232:233], v[232:233], s[30:31]
	v_rcp_f32_e32 v244, v244
	v_rcp_f32_e32 v245, v245
	v_rcp_f32_e32 v246, v246
	v_rcp_f32_e32 v247, v247
	v_exp_f32_e32 v250, v250
	v_exp_f32_e32 v251, v251
	v_exp_f32_e32 v230, v230
	v_exp_f32_e32 v231, v231
	v_exp_f32_e32 v252, v252
	v_exp_f32_e32 v253, v253
	v_exp_f32_e32 v232, v232
	v_exp_f32_e32 v233, v233
	v_pk_mul_f32 v[244:245], v[2:3], v[244:245]
	v_pk_mul_f32 v[246:247], v[6:7], v[246:247]
	v_pk_add_f32 v[250:251], v[250:251], s[34:35]
	v_pk_add_f32 v[230:231], v[230:231], s[34:35]
	v_pk_add_f32 v[252:253], v[252:253], s[34:35]
	v_pk_add_f32 v[232:233], v[232:233], s[34:35]
	v_rcp_f32_e32 v250, v250
	v_rcp_f32_e32 v251, v251
	v_rcp_f32_e32 v230, v230
	v_rcp_f32_e32 v231, v231
	v_rcp_f32_e32 v252, v252
	v_rcp_f32_e32 v253, v253
	v_rcp_f32_e32 v232, v232
	v_rcp_f32_e32 v233, v233
	v_pk_mul_f32 v[248:249], v[250:251], v[248:249]
	v_pk_mul_f32 v[228:229], v[230:231], v[228:229]
	v_pk_fma_f32 v[248:249], v[252:253], v[244:245], v[248:249]
	v_pk_fma_f32 v[228:229], v[232:233], v[246:247], v[228:229]
	v_cvt_pk_bf16_f32 v250, v248, v228
	v_cvt_pk_bf16_f32 v251, v249, v229
	s_add_u32 s2, s64, 0x165000
	s_addc_u32 s3, s65, 0
	global_store_dword v137, v250, s[2:3] offset:-4096 nt
	s_add_u32 s2, s64, 0x167000
	s_addc_u32 s3, s65, 0
	global_store_dword v137, v251, s[2:3] offset:-4096 nt
	s_mov_b32 s30, 0x80100
	s_mov_b32 s31, 0x20100
	s_mov_b32 s34, 0x30100
	s_mov_b32 s35, 0x100100
	s_add_i32 s12, s12, 1
	s_cmp_lg_u32 s12, 8
	s_cbranch_scc0 .LBB0_367
